# attention loop head aligned to 64 B; subtraction-free tail falls through, general tail out of line
# baseline (speedup 1.0000x reference)
; #define LAS __attribute__((address_space(3)))
; __device__ __forceinline__ int v_rd_base(int lane) { return ((lane & 3) << 3) | (((lane >> 2) & 3) << 6) | (((lane >> 4) & 1) << 5) | (((lane >> 5) & 1) << 8); }
; __device__ __forceinline__ void attn_unit(const bf16_t* __restrict__ Qb, const bf16_t* __restrict__ Kh, const bf16_t* __restrict__ Vh, bf16_t* __restrict__ Ob,
;                                           LAS unsigned char* lds, float MB, int tid, int nrows, int t0, int t1, float* part, float* partl) {
;     ...
;     float l_reg = 0.f; f32x16 o[4] = {}; bf16x8 qr[QREG];
;     LAS unsigned char* qt = lds + LDS_QT + wid * ((12 - QREG) * 1024) + lane * 16;
;     const unsigned qo = (unsigned)((wid * 32 + r32) * LDQ + hi * 8) * 2u;
; #pragma unroll
;     for (int d0 = 0; d0 < QREG; ++d0) qr[d0] = *(const bf16x8*)((const char*)Qb + qo + d0 * 32);
; #pragma unroll
;     for (int d0 = QREG; d0 < 12; ++d0) *(LAS bf16x8*)(qt + (d0 - QREG) * 1024) = *(const bf16x8*)((const char*)Qb + qo + d0 * 32);
;     unsigned ko[3], vo[2];
; #pragma unroll
;     for (int i = 0; i < 3; ++i) { const int sl = tid + 512 * i, row = sl / 24, pc = sl - row * 24, ch = pc ^ ((row >> 1) & 7); ko[i] = (unsigned)(row * LDKK + ch * 8) * 2u; }
; #pragma unroll
;     for (int i = 0; i < 2; ++i) { const int sl = tid + 512 * i, sub = sl >> 5, kk = (sub >> 2) * 8 + ((sl >> 2) & 7), c = (sub & 3) * 32 + (sl & 3) * 8;
;         const int kx = (kk & ~0xC) | ((kk & 4) << 1) | ((kk & 8) >> 1); vo[i] = (unsigned)(kx * LDV + c) * 2u; }
;     const int vb0 = (int)(unsigned)(uintptr_t)V_lds + v_rd_base(lane);
;     const unsigned ldw = (unsigned)wid * 1024u;
;     ...
;     f32x16 p0, p1; bf16x8 pa0, pa1, pa2, pa3;
;     SDMA(t0 * KVBLK, 0); asm volatile("s_waitcnt vmcnt(0)" ::: "memory"); __syncthreads();
.LBB0_136:
	v_mov_b32_e32 v147, v221
	v_mov_b32_e32 v213, v209
	v_mov_b32_e32 v214, v210
	s_mov_b32 s65, 0
	v_mov_b32_e32 v155, 0
	v_mov_b32_e32 v149, 0
	s_add_i32 s61, s58, 0x4000
	s_add_i32 s62, s58, 0x10000
	s_add_i32 s63, s58, 0x12000
	s_add_i32 s52, s52, 64
	s_mov_b32 s64, 0
	v_mov_b32_e32 v48, 0
	v_mov_b32_e32 v49, v155
	v_mov_b32_e32 v50, v155
	v_mov_b32_e32 v51, v155
	v_mov_b32_e32 v52, v155
	v_mov_b32_e32 v53, v155
	v_mov_b32_e32 v54, v155
	v_mov_b32_e32 v55, v155
	v_mov_b32_e32 v56, v155
	v_mov_b32_e32 v57, v155
	v_mov_b32_e32 v58, v155
	v_mov_b32_e32 v59, v155
	v_mov_b32_e32 v60, v155
	v_mov_b32_e32 v61, v155
	v_mov_b32_e32 v62, v155
	v_mov_b32_e32 v63, v155
	v_mov_b32_e32 v32, 0
	v_mov_b32_e32 v33, v155
	v_mov_b32_e32 v34, v155
	v_mov_b32_e32 v35, v155
	v_mov_b32_e32 v36, v155
	v_mov_b32_e32 v37, v155
	v_mov_b32_e32 v38, v155
	v_mov_b32_e32 v39, v155
	v_mov_b32_e32 v40, v155
	v_mov_b32_e32 v41, v155
	v_mov_b32_e32 v42, v155
	v_mov_b32_e32 v43, v155
	v_mov_b32_e32 v44, v155
	v_mov_b32_e32 v45, v155
	v_mov_b32_e32 v46, v155
	v_mov_b32_e32 v47, v155
	v_mov_b32_e32 v16, 0
	v_mov_b32_e32 v17, v155
	v_mov_b32_e32 v18, v155
	v_mov_b32_e32 v19, v155
	v_mov_b32_e32 v20, v155
	v_mov_b32_e32 v21, v155
	v_mov_b32_e32 v22, v155
	v_mov_b32_e32 v23, v155
	v_mov_b32_e32 v24, v155
	v_mov_b32_e32 v25, v155
	v_mov_b32_e32 v26, v155
	v_mov_b32_e32 v27, v155
	v_mov_b32_e32 v28, v155
	v_mov_b32_e32 v29, v155
	v_mov_b32_e32 v30, v155
	v_mov_b32_e32 v31, v155
	v_mov_b32_e32 v0, 0
	v_mov_b32_e32 v1, v155
	v_mov_b32_e32 v2, v155
	v_mov_b32_e32 v3, v155
	v_mov_b32_e32 v4, v155
	v_mov_b32_e32 v5, v155
	v_mov_b32_e32 v6, v155
	v_mov_b32_e32 v7, v155
	v_mov_b32_e32 v8, v155
	v_mov_b32_e32 v9, v155
	v_mov_b32_e32 v10, v155
	v_mov_b32_e32 v11, v155
	v_mov_b32_e32 v12, v155
	v_mov_b32_e32 v13, v155
	v_mov_b32_e32 v14, v155
	v_mov_b32_e32 v15, v155
	s_branch .LBB0_138
	.p2align 6

; #define LAS __attribute__((address_space(3)))
; #define SBAR() __builtin_amdgcn_sched_barrier(0)
; __device__ __forceinline__ void qkt(f32x16& p0, f32x16& p1, LAS const unsigned char* Ks, const bf16x8* qr, LAS const unsigned char* qt, int r32, int hi) {
;     p0 = (f32x16){}; p1 = (f32x16){};
; #pragma unroll
;     for (int d0 = 0; d0 < 12; ++d0) { const int cb = (d0 * 16 + hi * 8) * 2;
;         const bf16x8 b0 = *(const LAS bf16x8*)(Ks + KSWZ(r32, cb));
;         const bf16x8 b1 = *(const LAS bf16x8*)(Ks + KSWZ(32 + r32, cb));
;         const bf16x8 qf = d0 < QREG ? qr[d0 < QREG ? d0 : 0] : *(const LAS bf16x8*)(qt + (d0 - QREG) * 1024);
;         p0 = __builtin_amdgcn_mfma_f32_32x32x16_bf16(b0, qf, p0, 0, 0, 0);
;         p1 = __builtin_amdgcn_mfma_f32_32x32x16_bf16(b1, qf, p1, 0, 0, 0);
;         if ((d0 & 3) == 3) SBAR(); }
; }
; __device__ __forceinline__ void expP(f32x16& p0, f32x16& p1, float MB) {
; #pragma unroll
;     for (int r = 0; r < 16; ++r) p0[r] = __builtin_amdgcn_exp2f(p0[r] - MB);
; #pragma unroll
;     for (int r = 0; r < 16; ++r) p1[r] = __builtin_amdgcn_exp2f(p1[r] - MB);
; }
; __device__ __forceinline__ void maskLast(f32x16& p0, f32x16& p1) {
; #pragma unroll
;     for (int r = 8; r < 16; ++r) p0[r] = 0.f;
; #pragma unroll
;     for (int r = 0; r < 16; ++r) p1[r] = 0.f;
; }
; __device__ __forceinline__ void finishP(const f32x16& p0, const f32x16& p1, float& l_reg, bf16x8& pa0, bf16x8& pa1, bf16x8& pa2, bf16x8& pa3) {
;     float ps = 0.f;
; #pragma unroll
;     for (int r = 0; r < 16; ++r) ps += p0[r];
; #pragma unroll
;     for (int r = 0; r < 16; ++r) ps += p1[r];
;     l_reg += ps;
; __device__ __forceinline__ void attn_unit(const bf16_t* __restrict__ Qb, const bf16_t* __restrict__ Kh, const bf16_t* __restrict__ Vh, bf16_t* __restrict__ Ob,
;                                           LAS unsigned char* lds, float MB, int tid, int nrows, int t0, int t1, float* part, float* partl) {
;     ...
;     for (int j = t0; j < t1; ++j) {
;         const int b = (j - t0) & 1; const bool more = (j + 1 < t1);
;         if (more) { if (b) SDMA((j + 1) * KVBLK, 0); else SDMA((j + 1) * KVBLK, 1); }
;         if (act) {
;         SBAR(); qkt(p0, p1, K_lds + b * SHM_K, qr, qt, r32, hi);
;         expP(p0, p1, MB);
;         if (j == NT - 1) maskLast(p0, p1);
;         finishP(p0, p1, l_reg, pa0, pa1, pa2, pa3); SBAR();
.Latt_st2:
	s_andn2_b64 vcc, exec, s[50:51]
	s_cbranch_vccnz .Latt_inactive
	ds_read_b128 v[216:219], v213 offset:32768
	ds_read_b128 v[224:227], v214 offset:32768
	ds_read_b128 v[240:243], v213 offset:32896
	ds_read_b128 v[244:247], v214 offset:32896
	v_readfirstlane_b32 s70, v206
	s_nop 3
	s_cmpk_eq_i32 s66, 0x80
	s_cselect_b32 s66, 0x7f800000, s70
	s_add_i32 s67, s52, 64
	s_lshl_b32 s68, s67, 13
	s_mov_b32 s69, 0
	s_mul_i32 s43, s67, 0x1800
	s_add_u32 s70, s54, s43
	s_addc_u32 s71, s55, 0
	s_add_u32 s68, s56, s68
	s_addc_u32 s69, s57, s69
	s_add_i32 s53, s65, 2
	s_cmp_ge_u32 s53, 3
	s_cselect_b32 s42, 3, 0
	s_sub_i32 s53, s53, s42
	s_cmp_eq_u32 s53, 2
	s_cselect_b32 s42, 0x5000, 0
	s_cselect_b32 s43, 0xd000, 0
	s_mul_i32 s67, s53, 0x6000
	s_add_i32 s42, s42, s67
	s_add_i32 s42, s42, 0x8000
	s_add_i32 s42, s58, s42
	s_lshl_b32 s67, s53, 14
	s_add_i32 s43, s43, s67
	s_add_i32 s43, s58, s43
	s_waitcnt lgkmcnt(3)
	v_mfma_f32_16x16x32_bf16 v[64:67], v[216:219], v[96:99], 0
	v_mfma_f32_16x16x32_bf16 v[72:75], v[216:219], v[120:123], 0
	ds_read_b128 v[216:219], v213 offset:33024
	s_waitcnt lgkmcnt(3)
	v_mfma_f32_16x16x32_bf16 v[64:67], v[224:227], v[100:103], v[64:67]
	v_mfma_f32_16x16x32_bf16 v[72:75], v[224:227], v[124:127], v[72:75]
	ds_read_b128 v[224:227], v214 offset:33024
	s_waitcnt lgkmcnt(3)
	v_mfma_f32_16x16x32_bf16 v[64:67], v[240:243], v[104:107], v[64:67]
	v_lshl_add_u64 v[166:167], s[70:71], 0, v[156:157]
	s_mov_b32 m0, s42
	s_nop 0
	global_load_lds_dwordx4 v[166:167], off
	v_mfma_f32_16x16x32_bf16 v[72:75], v[240:243], v[128:131], v[72:75]
	ds_read_b128 v[240:243], v213 offset:38912
	s_waitcnt lgkmcnt(3)
	v_mfma_f32_16x16x32_bf16 v[64:67], v[244:247], v[108:111], v[64:67]
	v_mfma_f32_16x16x32_bf16 v[72:75], v[244:247], v[132:135], v[72:75]
	ds_read_b128 v[244:247], v214 offset:38912
	s_waitcnt lgkmcnt(3)
	v_mfma_f32_16x16x32_bf16 v[64:67], v[216:219], v[112:115], v[64:67]
	v_mfma_f32_16x16x32_bf16 v[72:75], v[216:219], v[136:139], v[72:75]
	ds_read_b128 v[216:219], v213 offset:39040
	s_waitcnt lgkmcnt(3)
	v_mfma_f32_16x16x32_bf16 v[64:67], v[224:227], v[116:119], v[64:67]
	v_mfma_f32_16x16x32_bf16 v[72:75], v[224:227], v[140:143], v[72:75]
	ds_read_b128 v[224:227], v214 offset:39040
	s_waitcnt lgkmcnt(3)
	v_mfma_f32_16x16x32_bf16 v[68:71], v[240:243], v[96:99], 0
	v_mfma_f32_16x16x32_bf16 v[76:79], v[240:243], v[120:123], 0
	ds_read_b128 v[240:243], v213 offset:39168
	s_waitcnt lgkmcnt(3)
	v_mfma_f32_16x16x32_bf16 v[68:71], v[244:247], v[100:103], v[68:71]
	v_mfma_f32_16x16x32_bf16 v[76:79], v[244:247], v[124:127], v[76:79]
	ds_read_b128 v[244:247], v214 offset:39168
	s_waitcnt lgkmcnt(3)
	v_mfma_f32_16x16x32_bf16 v[68:71], v[216:219], v[104:107], v[68:71]
	v_mfma_f32_16x16x32_bf16 v[76:79], v[216:219], v[128:131], v[76:79]
	ds_read_b128 v[216:219], v213 offset:45056
	s_waitcnt lgkmcnt(3)
	v_mfma_f32_16x16x32_bf16 v[68:71], v[224:227], v[108:111], v[68:71]
	v_mfma_f32_16x16x32_bf16 v[76:79], v[224:227], v[132:135], v[76:79]
	ds_read_b128 v[224:227], v214 offset:45056
	s_waitcnt lgkmcnt(3)
	v_mfma_f32_16x16x32_bf16 v[68:71], v[240:243], v[112:115], v[68:71]
	v_lshl_add_u64 v[166:167], s[70:71], 0, v[158:159]
	s_add_i32 m0, s42, 0x2000
	s_nop 0
	global_load_lds_dwordx4 v[166:167], off
	v_mfma_f32_16x16x32_bf16 v[76:79], v[240:243], v[136:139], v[76:79]
	ds_read_b128 v[240:243], v213 offset:45184
	s_waitcnt lgkmcnt(3)
	v_mfma_f32_16x16x32_bf16 v[68:71], v[244:247], v[116:119], v[68:71]
	v_mfma_f32_16x16x32_bf16 v[76:79], v[244:247], v[140:143], v[76:79]
	ds_read_b128 v[244:247], v214 offset:45184
	s_cmp_eq_u32 s66, 0
	s_cbranch_scc0 .Latt_general
	v_exp_f32_e32 v64, v64
	v_exp_f32_e32 v65, v65
	s_waitcnt lgkmcnt(3)
	v_mfma_f32_16x16x32_bf16 v[80:83], v[216:219], v[96:99], 0
	v_exp_f32_e32 v66, v66
	v_exp_f32_e32 v67, v67
	v_mfma_f32_16x16x32_bf16 v[88:91], v[216:219], v[120:123], 0
	ds_read_b128 v[216:219], v213 offset:45312
	v_add_f32_e32 v146, v64, v65
	v_exp_f32_e32 v68, v68
	s_waitcnt lgkmcnt(3)
	v_mfma_f32_16x16x32_bf16 v[80:83], v[224:227], v[100:103], v[80:83]
	v_add_f32_e32 v146, v66, v146
	v_exp_f32_e32 v69, v69
	v_mfma_f32_16x16x32_bf16 v[88:91], v[224:227], v[124:127], v[88:91]
	ds_read_b128 v[224:227], v214 offset:45312
	v_add_f32_e32 v146, v67, v146
	v_exp_f32_e32 v70, v70
	s_waitcnt lgkmcnt(3)
	v_mfma_f32_16x16x32_bf16 v[80:83], v[240:243], v[104:107], v[80:83]
	v_add_f32_e32 v146, v68, v146
	v_exp_f32_e32 v71, v71
	v_mfma_f32_16x16x32_bf16 v[88:91], v[240:243], v[128:131], v[88:91]
	ds_read_b128 v[240:243], v213 offset:51200
	v_add_f32_e32 v146, v69, v146
	v_add_f32_e32 v146, v70, v146
	s_waitcnt lgkmcnt(3)
	v_mfma_f32_16x16x32_bf16 v[80:83], v[244:247], v[108:111], v[80:83]
	v_add_f32_e32 v146, v71, v146
	v_cvt_pk_bf16_f32 v64, v64, v65
	v_mfma_f32_16x16x32_bf16 v[88:91], v[244:247], v[132:135], v[88:91]
	ds_read_b128 v[244:247], v214 offset:51200
	v_cvt_pk_bf16_f32 v65, v66, v67
	v_cvt_pk_bf16_f32 v66, v68, v69
	s_waitcnt lgkmcnt(3)
	v_mfma_f32_16x16x32_bf16 v[80:83], v[216:219], v[112:115], v[80:83]
	v_cvt_pk_bf16_f32 v67, v70, v71
	v_exp_f32_e32 v72, v72
	ds_read_b128 v[68:71], v213 offset:51328
	v_mfma_f32_16x16x32_bf16 v[88:91], v[216:219], v[136:139], v[88:91]
	ds_read_b128 v[216:219], v214 offset:51328
	v_exp_f32_e32 v73, v73
	v_exp_f32_e32 v74, v74
	s_waitcnt lgkmcnt(4)
	v_mfma_f32_16x16x32_bf16 v[80:83], v[224:227], v[116:119], v[80:83]
	v_exp_f32_e32 v75, v75
	v_add_f32_e32 v148, v72, v73
	v_mfma_f32_16x16x32_bf16 v[88:91], v[224:227], v[140:143], v[88:91]
	ds_read_b128 v[224:227], v213 offset:51456
	v_exp_f32_e32 v76, v76
	v_add_f32_e32 v148, v74, v148
	s_waitcnt lgkmcnt(4)
; #define LAS __attribute__((address_space(3)))
; #define SBAR() __builtin_amdgcn_sched_barrier(0)
; __device__ __forceinline__ void pv_d0(f32x16* o, int vb, bf16x8 pa0, bf16x8 pa1, bf16x8 pa2, bf16x8 pa3) {
;     VBlk A, B;
;     pv_load<0>(A, vb); pv_load<1>(B, vb);
;     asm volatile("s_waitcnt lgkmcnt(8)" ::: "memory"); SBAR(); pv_mma(o[0], A, pa0, pa1, pa2, pa3); SBAR();
;     pv_load<2>(A, vb);
;     asm volatile("s_waitcnt lgkmcnt(8)" ::: "memory"); SBAR(); pv_mma(o[1], B, pa0, pa1, pa2, pa3); SBAR();
;     pv_load<3>(B, vb);
;     asm volatile("s_waitcnt lgkmcnt(8)" ::: "memory"); SBAR(); pv_mma(o[2], A, pa0, pa1, pa2, pa3); SBAR();
;     asm volatile("s_waitcnt lgkmcnt(0)" ::: "memory"); SBAR(); pv_mma(o[3], B, pa0, pa1, pa2, pa3); SBAR();
; }
; __device__ __forceinline__ void qkt(f32x16& p0, f32x16& p1, LAS const unsigned char* Ks, const bf16x8* qr, LAS const unsigned char* qt, int r32, int hi) {
;     p0 = (f32x16){}; p1 = (f32x16){};
; #pragma unroll
;     for (int d0 = 0; d0 < 12; ++d0) { const int cb = (d0 * 16 + hi * 8) * 2;
;         const bf16x8 b0 = *(const LAS bf16x8*)(Ks + KSWZ(r32, cb));
;         const bf16x8 b1 = *(const LAS bf16x8*)(Ks + KSWZ(32 + r32, cb));
;         const bf16x8 qf = d0 < QREG ? qr[d0 < QREG ? d0 : 0] : *(const LAS bf16x8*)(qt + (d0 - QREG) * 1024);
;         p0 = __builtin_amdgcn_mfma_f32_32x32x16_bf16(b0, qf, p0, 0, 0, 0);
;         p1 = __builtin_amdgcn_mfma_f32_32x32x16_bf16(b1, qf, p1, 0, 0, 0);
;         if ((d0 & 3) == 3) SBAR(); }
; }
; __device__ __forceinline__ void expP(f32x16& p0, f32x16& p1, float MB) {
; #pragma unroll
;     for (int r = 0; r < 16; ++r) p0[r] = __builtin_amdgcn_exp2f(p0[r] - MB);
; #pragma unroll
;     for (int r = 0; r < 16; ++r) p1[r] = __builtin_amdgcn_exp2f(p1[r] - MB);
; }
; __device__ __forceinline__ void maskLast(f32x16& p0, f32x16& p1) {
; #pragma unroll
;     for (int r = 8; r < 16; ++r) p0[r] = 0.f;
; #pragma unroll
;     for (int r = 0; r < 16; ++r) p1[r] = 0.f;
; }
; __device__ __forceinline__ void finishP(const f32x16& p0, const f32x16& p1, float& l_reg, bf16x8& pa0, bf16x8& pa1, bf16x8& pa2, bf16x8& pa3) {
;     float ps = 0.f;
; #pragma unroll
;     for (int r = 0; r < 16; ++r) ps += p0[r];
; #pragma unroll
;     for (int r = 0; r < 16; ++r) ps += p1[r];
;     l_reg += ps;
;     ...
;     PK4(p0, 0, pa0); PK4(p0, 8, pa1); PK4(p1, 0, pa2); PK4(p1, 8, pa3);
;     ...
; }
	v_mfma_f32_16x16x32_bf16 v[84:87], v[240:243], v[96:99], 0
	v_lshl_add_u64 v[166:167], s[70:71], 0, v[160:161]
	s_add_i32 m0, s42, 0x4000
	s_nop 0
	global_load_lds_dwordx4 v[166:167], off
	v_exp_f32_e32 v77, v77
	v_add_f32_e32 v148, v75, v148
	v_mfma_f32_16x16x32_bf16 v[92:95], v[240:243], v[120:123], 0
	ds_read_b128 v[240:243], v214 offset:51456
	v_exp_f32_e32 v78, v78
	s_waitcnt lgkmcnt(4)
	v_mfma_f32_16x16x32_bf16 v[84:87], v[244:247], v[100:103], v[84:87]
	v_add_f32_e32 v148, v76, v148
	v_mfma_f32_16x16x32_bf16 v[92:95], v[244:247], v[124:127], v[92:95]
	ds_read_b64_tr_b16 v[244:245], v147 offset:0
	ds_read_b64_tr_b16 v[246:247], v147 offset:4096
	v_exp_f32_e32 v79, v79
	s_waitcnt lgkmcnt(5)
	v_mfma_f32_16x16x32_bf16 v[84:87], v[68:71], v[104:107], v[84:87]
	v_add_f32_e32 v148, v77, v148
	v_mfma_f32_16x16x32_bf16 v[92:95], v[68:71], v[128:131], v[92:95]
	ds_read_b64_tr_b16 v[68:69], v147 offset:256
	ds_read_b64_tr_b16 v[70:71], v147 offset:4352
	v_add_f32_e32 v148, v78, v148
	s_waitcnt lgkmcnt(6)
	v_mfma_f32_16x16x32_bf16 v[84:87], v[216:219], v[108:111], v[84:87]
	v_add_f32_e32 v148, v79, v148
	v_mfma_f32_16x16x32_bf16 v[92:95], v[216:219], v[132:135], v[92:95]
	ds_read_b64_tr_b16 v[216:217], v147 offset:512
	ds_read_b64_tr_b16 v[218:219], v147 offset:4608
	v_cvt_pk_bf16_f32 v72, v72, v73
	s_waitcnt lgkmcnt(7)
	v_mfma_f32_16x16x32_bf16 v[84:87], v[224:227], v[112:115], v[84:87]
	v_cvt_pk_bf16_f32 v73, v74, v75
	v_mfma_f32_16x16x32_bf16 v[92:95], v[224:227], v[136:139], v[92:95]
	ds_read_b64_tr_b16 v[224:225], v147 offset:768
	ds_read_b64_tr_b16 v[226:227], v147 offset:4864
	v_cvt_pk_bf16_f32 v74, v76, v77
	s_waitcnt lgkmcnt(8)
	v_mfma_f32_16x16x32_bf16 v[84:87], v[240:243], v[116:119], v[84:87]
	v_cvt_pk_bf16_f32 v75, v78, v79
	ds_read_b64_tr_b16 v[76:77], v147 offset:1024
	ds_read_b64_tr_b16 v[78:79], v147 offset:5120
	v_mfma_f32_16x16x32_bf16 v[92:95], v[240:243], v[140:143], v[92:95]
	ds_read_b64_tr_b16 v[240:241], v147 offset:1280
	ds_read_b64_tr_b16 v[242:243], v147 offset:5376
	v_exp_f32_e32 v80, v80
	v_exp_f32_e32 v81, v81
	v_exp_f32_e32 v82, v82
	s_waitcnt lgkmcnt(10)
	v_mfma_f32_16x16x32_bf16 v[0:3], v[64:67], v[244:247], v[0:3]
	v_add_f32_e32 v146, v80, v146
	v_exp_f32_e32 v83, v83
	v_add_f32_e32 v146, v81, v146
	v_mfma_f32_16x16x32_bf16 v[32:35], v[72:75], v[244:247], v[32:35]
	ds_read_b64_tr_b16 v[244:245], v147 offset:1536
	ds_read_b64_tr_b16 v[246:247], v147 offset:5632
	v_exp_f32_e32 v84, v84
	v_add_f32_e32 v146, v82, v146
	v_exp_f32_e32 v85, v85
	s_waitcnt lgkmcnt(10)
	v_mfma_f32_16x16x32_bf16 v[4:7], v[64:67], v[68:71], v[4:7]
	v_add_f32_e32 v146, v83, v146
	v_exp_f32_e32 v86, v86
	v_add_f32_e32 v146, v84, v146
	v_mfma_f32_16x16x32_bf16 v[36:39], v[72:75], v[68:71], v[36:39]
	ds_read_b64_tr_b16 v[68:69], v147 offset:1792
	ds_read_b64_tr_b16 v[70:71], v147 offset:5888
	v_exp_f32_e32 v87, v87
	v_add_f32_e32 v146, v85, v146
	v_add_f32_e32 v146, v86, v146
	s_waitcnt lgkmcnt(10)
	v_mfma_f32_16x16x32_bf16 v[8:11], v[64:67], v[216:219], v[8:11]
	v_lshl_add_u64 v[166:167], s[68:69], 0, v[162:163]
	s_mov_b32 m0, s43
	v_lshl_add_u64 v[166:167], v[166:167], 0, s[20:21]
	global_load_lds_dwordx4 v[166:167], off
	v_add_f32_e32 v146, v87, v146
	v_cvt_pk_bf16_f32 v80, v80, v81
	v_cvt_pk_bf16_f32 v81, v82, v83
	v_mfma_f32_16x16x32_bf16 v[40:43], v[72:75], v[216:219], v[40:43]
	ds_read_b64_tr_b16 v[216:217], v147 offset:8192
	ds_read_b64_tr_b16 v[218:219], v147 offset:12288
	v_cvt_pk_bf16_f32 v82, v84, v85
	v_cvt_pk_bf16_f32 v83, v86, v87
	v_add_f32_e32 v155, v155, v146
	ds_read_b64_tr_b16 v[84:85], v147 offset:8448
	ds_read_b64_tr_b16 v[86:87], v147 offset:12544
	s_waitcnt lgkmcnt(12)
	v_mfma_f32_16x16x32_bf16 v[12:15], v[64:67], v[224:227], v[12:15]
	v_exp_f32_e32 v88, v88
	v_exp_f32_e32 v89, v89
	v_exp_f32_e32 v90, v90
	v_mfma_f32_16x16x32_bf16 v[44:47], v[72:75], v[224:227], v[44:47]
	ds_read_b64_tr_b16 v[224:225], v147 offset:8704
	ds_read_b64_tr_b16 v[226:227], v147 offset:12800
	v_add_f32_e32 v148, v88, v148
	v_exp_f32_e32 v91, v91
	v_add_f32_e32 v148, v89, v148
	s_waitcnt lgkmcnt(12)
	v_mfma_f32_16x16x32_bf16 v[16:19], v[64:67], v[76:79], v[16:19]
	v_exp_f32_e32 v92, v92
	v_add_f32_e32 v148, v90, v148
	v_exp_f32_e32 v93, v93
	v_mfma_f32_16x16x32_bf16 v[48:51], v[72:75], v[76:79], v[48:51]
	ds_read_b64_tr_b16 v[76:77], v147 offset:8960
	ds_read_b64_tr_b16 v[78:79], v147 offset:13056
	v_add_f32_e32 v148, v91, v148
	v_exp_f32_e32 v94, v94
	s_waitcnt lgkmcnt(12)
	v_mfma_f32_16x16x32_bf16 v[20:23], v[64:67], v[240:243], v[20:23]
	v_add_f32_e32 v148, v92, v148
	v_exp_f32_e32 v95, v95
	v_mfma_f32_16x16x32_bf16 v[52:55], v[72:75], v[240:243], v[52:55]
	ds_read_b64_tr_b16 v[240:241], v147 offset:9216
	ds_read_b64_tr_b16 v[242:243], v147 offset:13312
	v_add_f32_e32 v148, v93, v148
	v_add_f32_e32 v148, v94, v148
	s_waitcnt lgkmcnt(12)
	v_mfma_f32_16x16x32_bf16 v[24:27], v[64:67], v[244:247], v[24:27]
	v_add_f32_e32 v148, v95, v148
	v_cvt_pk_bf16_f32 v88, v88, v89
	v_mfma_f32_16x16x32_bf16 v[56:59], v[72:75], v[244:247], v[56:59]
	ds_read_b64_tr_b16 v[244:245], v147 offset:9472
	ds_read_b64_tr_b16 v[246:247], v147 offset:13568
	v_cvt_pk_bf16_f32 v89, v90, v91
	v_cvt_pk_bf16_f32 v90, v92, v93
	s_waitcnt lgkmcnt(12)
	v_mfma_f32_16x16x32_bf16 v[28:31], v[64:67], v[68:71], v[28:31]
	v_cvt_pk_bf16_f32 v91, v94, v95
	v_add_f32_e32 v149, v149, v148
	ds_read_b64_tr_b16 v[92:93], v147 offset:9728
	ds_read_b64_tr_b16 v[94:95], v147 offset:13824
	v_mfma_f32_16x16x32_bf16 v[60:63], v[72:75], v[68:71], v[60:63]
	s_waitcnt lgkmcnt(12)
	v_mfma_f32_16x16x32_bf16 v[0:3], v[80:83], v[216:219], v[0:3]
	v_mfma_f32_16x16x32_bf16 v[32:35], v[88:91], v[216:219], v[32:35]
	ds_read_b64_tr_b16 v[68:69], v147 offset:9984
	ds_read_b64_tr_b16 v[70:71], v147 offset:14080
	s_waitcnt lgkmcnt(12)
	v_mfma_f32_16x16x32_bf16 v[4:7], v[80:83], v[84:87], v[4:7]
	v_mfma_f32_16x16x32_bf16 v[36:39], v[88:91], v[84:87], v[36:39]
	s_waitcnt lgkmcnt(10)
	v_mfma_f32_16x16x32_bf16 v[8:11], v[80:83], v[224:227], v[8:11]
	v_lshl_add_u64 v[166:167], s[68:69], 0, v[164:165]
	s_add_i32 m0, s43, 0x2000
	v_lshl_add_u64 v[166:167], v[166:167], 0, s[20:21]
	global_load_lds_dwordx4 v[166:167], off
	v_mfma_f32_16x16x32_bf16 v[40:43], v[88:91], v[224:227], v[40:43]
	s_waitcnt lgkmcnt(8)
	v_mfma_f32_16x16x32_bf16 v[12:15], v[80:83], v[76:79], v[12:15]
	v_mfma_f32_16x16x32_bf16 v[44:47], v[88:91], v[76:79], v[44:47]
	s_waitcnt lgkmcnt(6)
	v_mfma_f32_16x16x32_bf16 v[16:19], v[80:83], v[240:243], v[16:19]
	v_mfma_f32_16x16x32_bf16 v[48:51], v[88:91], v[240:243], v[48:51]
	s_waitcnt lgkmcnt(4)
	v_mfma_f32_16x16x32_bf16 v[20:23], v[80:83], v[244:247], v[20:23]
	v_mfma_f32_16x16x32_bf16 v[52:55], v[88:91], v[244:247], v[52:55]
	s_waitcnt lgkmcnt(2)
	v_mfma_f32_16x16x32_bf16 v[24:27], v[80:83], v[92:95], v[24:27]
	v_mfma_f32_16x16x32_bf16 v[56:59], v[88:91], v[92:95], v[56:59]
	s_waitcnt lgkmcnt(0)
	v_mfma_f32_16x16x32_bf16 v[28:31], v[80:83], v[68:71], v[28:31]
	v_mfma_f32_16x16x32_bf16 v[60:63], v[88:91], v[68:71], v[60:63]
	s_mov_b32 s71, 1
	s_branch .LBB0_137

; #define LAS __attribute__((address_space(3)))
; #define SBAR() __builtin_amdgcn_sched_barrier(0)
; __device__ __forceinline__ void pv_d0(f32x16* o, int vb, bf16x8 pa0, bf16x8 pa1, bf16x8 pa2, bf16x8 pa3) {
;     VBlk A, B;
;     pv_load<0>(A, vb); pv_load<1>(B, vb);
;     asm volatile("s_waitcnt lgkmcnt(8)" ::: "memory"); SBAR(); pv_mma(o[0], A, pa0, pa1, pa2, pa3); SBAR();
;     pv_load<2>(A, vb);
;     asm volatile("s_waitcnt lgkmcnt(8)" ::: "memory"); SBAR(); pv_mma(o[1], B, pa0, pa1, pa2, pa3); SBAR();
;     pv_load<3>(B, vb);
;     asm volatile("s_waitcnt lgkmcnt(8)" ::: "memory"); SBAR(); pv_mma(o[2], A, pa0, pa1, pa2, pa3); SBAR();
;     asm volatile("s_waitcnt lgkmcnt(0)" ::: "memory"); SBAR(); pv_mma(o[3], B, pa0, pa1, pa2, pa3); SBAR();
; }
; __device__ __forceinline__ void qkt(f32x16& p0, f32x16& p1, LAS const unsigned char* Ks, const bf16x8* qr, LAS const unsigned char* qt, int r32, int hi) {
;     p0 = (f32x16){}; p1 = (f32x16){};
; #pragma unroll
;     for (int d0 = 0; d0 < 12; ++d0) { const int cb = (d0 * 16 + hi * 8) * 2;
;         const bf16x8 b0 = *(const LAS bf16x8*)(Ks + KSWZ(r32, cb));
;         const bf16x8 b1 = *(const LAS bf16x8*)(Ks + KSWZ(32 + r32, cb));
;         const bf16x8 qf = d0 < QREG ? qr[d0 < QREG ? d0 : 0] : *(const LAS bf16x8*)(qt + (d0 - QREG) * 1024);
;         p0 = __builtin_amdgcn_mfma_f32_32x32x16_bf16(b0, qf, p0, 0, 0, 0);
;         p1 = __builtin_amdgcn_mfma_f32_32x32x16_bf16(b1, qf, p1, 0, 0, 0);
;         if ((d0 & 3) == 3) SBAR(); }
; }
; __device__ __forceinline__ void expP(f32x16& p0, f32x16& p1, float MB) {
; #pragma unroll
;     for (int r = 0; r < 16; ++r) p0[r] = __builtin_amdgcn_exp2f(p0[r] - MB);
; #pragma unroll
;     for (int r = 0; r < 16; ++r) p1[r] = __builtin_amdgcn_exp2f(p1[r] - MB);
; }
; __device__ __forceinline__ void maskLast(f32x16& p0, f32x16& p1) {
; #pragma unroll
;     for (int r = 8; r < 16; ++r) p0[r] = 0.f;
; #pragma unroll
;     for (int r = 0; r < 16; ++r) p1[r] = 0.f;
; }
; __device__ __forceinline__ void finishP(const f32x16& p0, const f32x16& p1, float& l_reg, bf16x8& pa0, bf16x8& pa1, bf16x8& pa2, bf16x8& pa3) {
;     float ps = 0.f;
; #pragma unroll
;     for (int r = 0; r < 16; ++r) ps += p0[r];
; #pragma unroll
;     for (int r = 0; r < 16; ++r) ps += p1[r];
;     l_reg += ps;
;     ...
;     PK4(p0, 0, pa0); PK4(p0, 8, pa1); PK4(p1, 0, pa2); PK4(p1, 8, pa3);
;     ...
; }
.Latt_general:
	v_sub_f32_e32 v64, v64, v206
	v_sub_f32_e32 v65, v65, v206
	v_exp_f32_e32 v64, v64
	s_waitcnt lgkmcnt(3)
	v_mfma_f32_16x16x32_bf16 v[80:83], v[216:219], v[96:99], 0
	v_sub_f32_e32 v66, v66, v206
	v_exp_f32_e32 v65, v65
	v_sub_f32_e32 v67, v67, v206
	v_mfma_f32_16x16x32_bf16 v[88:91], v[216:219], v[120:123], 0
	ds_read_b128 v[216:219], v213 offset:45312
	v_exp_f32_e32 v66, v66
	v_subrev_f32_e32 v68, s66, v68
	v_exp_f32_e32 v67, v67
	s_waitcnt lgkmcnt(3)
	v_mfma_f32_16x16x32_bf16 v[80:83], v[224:227], v[100:103], v[80:83]
	v_add_f32_e32 v146, v64, v65
	v_subrev_f32_e32 v69, s66, v69
	v_exp_f32_e32 v68, v68
	v_mfma_f32_16x16x32_bf16 v[88:91], v[224:227], v[124:127], v[88:91]
	ds_read_b128 v[224:227], v214 offset:45312
	v_add_f32_e32 v146, v66, v146
	v_subrev_f32_e32 v70, s66, v70
	v_exp_f32_e32 v69, v69
	s_waitcnt lgkmcnt(3)
	v_mfma_f32_16x16x32_bf16 v[80:83], v[240:243], v[104:107], v[80:83]
	v_add_f32_e32 v146, v67, v146
	v_subrev_f32_e32 v71, s66, v71
	v_exp_f32_e32 v70, v70
	v_mfma_f32_16x16x32_bf16 v[88:91], v[240:243], v[128:131], v[88:91]
	ds_read_b128 v[240:243], v213 offset:51200
	v_add_f32_e32 v146, v68, v146
	v_exp_f32_e32 v71, v71
	s_waitcnt lgkmcnt(3)
	v_mfma_f32_16x16x32_bf16 v[80:83], v[244:247], v[108:111], v[80:83]
	v_add_f32_e32 v146, v69, v146
	v_add_f32_e32 v146, v70, v146
	v_mfma_f32_16x16x32_bf16 v[88:91], v[244:247], v[132:135], v[88:91]
	ds_read_b128 v[244:247], v214 offset:51200
	v_add_f32_e32 v146, v71, v146
	v_cvt_pk_bf16_f32 v64, v64, v65
	s_waitcnt lgkmcnt(3)
	v_mfma_f32_16x16x32_bf16 v[80:83], v[216:219], v[112:115], v[80:83]
	v_cvt_pk_bf16_f32 v65, v66, v67
	v_cvt_pk_bf16_f32 v66, v68, v69
	v_mfma_f32_16x16x32_bf16 v[88:91], v[216:219], v[136:139], v[88:91]
	ds_read_b128 v[216:219], v213 offset:51328
	v_cvt_pk_bf16_f32 v67, v70, v71
	v_sub_f32_e32 v72, v72, v206
	ds_read_b128 v[68:71], v214 offset:51328
	s_waitcnt lgkmcnt(4)
	v_mfma_f32_16x16x32_bf16 v[80:83], v[224:227], v[116:119], v[80:83]
	v_sub_f32_e32 v73, v73, v206
	v_exp_f32_e32 v72, v72
	v_mfma_f32_16x16x32_bf16 v[88:91], v[224:227], v[140:143], v[88:91]
	ds_read_b128 v[224:227], v213 offset:51456
	v_sub_f32_e32 v74, v74, v206
	v_exp_f32_e32 v73, v73
	s_waitcnt lgkmcnt(4)
	v_mfma_f32_16x16x32_bf16 v[84:87], v[240:243], v[96:99], 0
	v_lshl_add_u64 v[166:167], s[70:71], 0, v[160:161]
	s_add_i32 m0, s42, 0x4000
	s_nop 0
	global_load_lds_dwordx4 v[166:167], off
	v_sub_f32_e32 v75, v75, v206
	v_exp_f32_e32 v74, v74
	v_mfma_f32_16x16x32_bf16 v[92:95], v[240:243], v[120:123], 0
	ds_read_b128 v[240:243], v214 offset:51456
	v_subrev_f32_e32 v76, s66, v76
	v_exp_f32_e32 v75, v75
	s_waitcnt lgkmcnt(4)
	v_mfma_f32_16x16x32_bf16 v[84:87], v[244:247], v[100:103], v[84:87]
	v_add_f32_e32 v148, v72, v73
	v_subrev_f32_e32 v77, s66, v77
	v_mfma_f32_16x16x32_bf16 v[92:95], v[244:247], v[124:127], v[92:95]
	ds_read_b64_tr_b16 v[244:245], v147 offset:0
	ds_read_b64_tr_b16 v[246:247], v147 offset:4096
	v_exp_f32_e32 v76, v76
	v_add_f32_e32 v148, v74, v148
	s_waitcnt lgkmcnt(5)
	v_mfma_f32_16x16x32_bf16 v[84:87], v[216:219], v[104:107], v[84:87]
	v_subrev_f32_e32 v78, s66, v78
	v_exp_f32_e32 v77, v77
	v_mfma_f32_16x16x32_bf16 v[92:95], v[216:219], v[128:131], v[92:95]
	ds_read_b64_tr_b16 v[216:217], v147 offset:256
	ds_read_b64_tr_b16 v[218:219], v147 offset:4352
	v_add_f32_e32 v148, v75, v148
	v_subrev_f32_e32 v79, s66, v79
	s_waitcnt lgkmcnt(6)
	v_mfma_f32_16x16x32_bf16 v[84:87], v[68:71], v[108:111], v[84:87]
	v_exp_f32_e32 v78, v78
	v_add_f32_e32 v148, v76, v148
	v_mfma_f32_16x16x32_bf16 v[92:95], v[68:71], v[132:135], v[92:95]
	ds_read_b64_tr_b16 v[68:69], v147 offset:512
	ds_read_b64_tr_b16 v[70:71], v147 offset:4608
	v_exp_f32_e32 v79, v79
	v_add_f32_e32 v148, v77, v148
	s_waitcnt lgkmcnt(7)
	v_mfma_f32_16x16x32_bf16 v[84:87], v[224:227], v[112:115], v[84:87]
	v_add_f32_e32 v148, v78, v148
	v_add_f32_e32 v148, v79, v148
	v_mfma_f32_16x16x32_bf16 v[92:95], v[224:227], v[136:139], v[92:95]
	ds_read_b64_tr_b16 v[224:225], v147 offset:768
	ds_read_b64_tr_b16 v[226:227], v147 offset:4864
	v_cvt_pk_bf16_f32 v72, v72, v73
	v_cvt_pk_bf16_f32 v73, v74, v75
	s_waitcnt lgkmcnt(8)
	v_mfma_f32_16x16x32_bf16 v[84:87], v[240:243], v[116:119], v[84:87]
	v_cvt_pk_bf16_f32 v74, v76, v77
	v_cvt_pk_bf16_f32 v75, v78, v79
	ds_read_b64_tr_b16 v[76:77], v147 offset:1024
	ds_read_b64_tr_b16 v[78:79], v147 offset:5120
	v_mfma_f32_16x16x32_bf16 v[92:95], v[240:243], v[140:143], v[92:95]
	ds_read_b64_tr_b16 v[240:241], v147 offset:1280
	ds_read_b64_tr_b16 v[242:243], v147 offset:5376
	v_subrev_f32_e32 v80, s66, v80
	v_subrev_f32_e32 v81, s66, v81
	v_exp_f32_e32 v80, v80
	v_subrev_f32_e32 v82, s66, v82
	s_waitcnt lgkmcnt(10)
	v_mfma_f32_16x16x32_bf16 v[0:3], v[64:67], v[244:247], v[0:3]
	v_exp_f32_e32 v81, v81
	v_subrev_f32_e32 v83, s66, v83
	v_exp_f32_e32 v82, v82
	v_add_f32_e32 v146, v80, v146
	v_mfma_f32_16x16x32_bf16 v[32:35], v[72:75], v[244:247], v[32:35]
	ds_read_b64_tr_b16 v[244:245], v147 offset:1536
	ds_read_b64_tr_b16 v[246:247], v147 offset:5632
	v_subrev_f32_e32 v84, s66, v84
	v_exp_f32_e32 v83, v83
	v_add_f32_e32 v146, v81, v146
	v_subrev_f32_e32 v85, s66, v85
	s_waitcnt lgkmcnt(10)
; #define LAS __attribute__((address_space(3)))
; #define SBAR() __builtin_amdgcn_sched_barrier(0)
; __device__ __forceinline__ void pv_d0(f32x16* o, int vb, bf16x8 pa0, bf16x8 pa1, bf16x8 pa2, bf16x8 pa3) {
;     VBlk A, B;
;     pv_load<0>(A, vb); pv_load<1>(B, vb);
;     asm volatile("s_waitcnt lgkmcnt(8)" ::: "memory"); SBAR(); pv_mma(o[0], A, pa0, pa1, pa2, pa3); SBAR();
;     pv_load<2>(A, vb);
;     asm volatile("s_waitcnt lgkmcnt(8)" ::: "memory"); SBAR(); pv_mma(o[1], B, pa0, pa1, pa2, pa3); SBAR();
;     pv_load<3>(B, vb);
;     asm volatile("s_waitcnt lgkmcnt(8)" ::: "memory"); SBAR(); pv_mma(o[2], A, pa0, pa1, pa2, pa3); SBAR();
;     asm volatile("s_waitcnt lgkmcnt(0)" ::: "memory"); SBAR(); pv_mma(o[3], B, pa0, pa1, pa2, pa3); SBAR();
; }
; __device__ __forceinline__ void qkt(f32x16& p0, f32x16& p1, LAS const unsigned char* Ks, const bf16x8* qr, LAS const unsigned char* qt, int r32, int hi) {
;     p0 = (f32x16){}; p1 = (f32x16){};
; #pragma unroll
;     for (int d0 = 0; d0 < 12; ++d0) { const int cb = (d0 * 16 + hi * 8) * 2;
;         const bf16x8 b0 = *(const LAS bf16x8*)(Ks + KSWZ(r32, cb));
;         const bf16x8 b1 = *(const LAS bf16x8*)(Ks + KSWZ(32 + r32, cb));
;         const bf16x8 qf = d0 < QREG ? qr[d0 < QREG ? d0 : 0] : *(const LAS bf16x8*)(qt + (d0 - QREG) * 1024);
;         p0 = __builtin_amdgcn_mfma_f32_32x32x16_bf16(b0, qf, p0, 0, 0, 0);
;         p1 = __builtin_amdgcn_mfma_f32_32x32x16_bf16(b1, qf, p1, 0, 0, 0);
;         if ((d0 & 3) == 3) SBAR(); }
; }
; __device__ __forceinline__ void expP(f32x16& p0, f32x16& p1, float MB) {
; #pragma unroll
;     for (int r = 0; r < 16; ++r) p0[r] = __builtin_amdgcn_exp2f(p0[r] - MB);
; #pragma unroll
;     for (int r = 0; r < 16; ++r) p1[r] = __builtin_amdgcn_exp2f(p1[r] - MB);
; }
; __device__ __forceinline__ void maskLast(f32x16& p0, f32x16& p1) {
; #pragma unroll
;     for (int r = 8; r < 16; ++r) p0[r] = 0.f;
; #pragma unroll
;     for (int r = 0; r < 16; ++r) p1[r] = 0.f;
; }
; __device__ __forceinline__ void finishP(const f32x16& p0, const f32x16& p1, float& l_reg, bf16x8& pa0, bf16x8& pa1, bf16x8& pa2, bf16x8& pa3) {
;     float ps = 0.f;
; #pragma unroll
;     for (int r = 0; r < 16; ++r) ps += p0[r];
; #pragma unroll
;     for (int r = 0; r < 16; ++r) ps += p1[r];
;     l_reg += ps;
;     ...
;     PK4(p0, 0, pa0); PK4(p0, 8, pa1); PK4(p1, 0, pa2); PK4(p1, 8, pa3);
;     ...
; }
	v_mfma_f32_16x16x32_bf16 v[4:7], v[64:67], v[216:219], v[4:7]
	v_exp_f32_e32 v84, v84
	v_add_f32_e32 v146, v82, v146
	v_subrev_f32_e32 v86, s66, v86
	v_exp_f32_e32 v85, v85
	v_mfma_f32_16x16x32_bf16 v[36:39], v[72:75], v[216:219], v[36:39]
	ds_read_b64_tr_b16 v[216:217], v147 offset:1792
	ds_read_b64_tr_b16 v[218:219], v147 offset:5888
	v_add_f32_e32 v146, v83, v146
	v_subrev_f32_e32 v87, s66, v87
	v_exp_f32_e32 v86, v86
	v_add_f32_e32 v146, v84, v146
	s_waitcnt lgkmcnt(10)
	v_mfma_f32_16x16x32_bf16 v[8:11], v[64:67], v[68:71], v[8:11]
	v_lshl_add_u64 v[166:167], s[68:69], 0, v[162:163]
	s_mov_b32 m0, s43
	v_lshl_add_u64 v[166:167], v[166:167], 0, s[20:21]
	global_load_lds_dwordx4 v[166:167], off
	v_exp_f32_e32 v87, v87
	v_add_f32_e32 v146, v85, v146
	v_add_f32_e32 v146, v86, v146
	v_add_f32_e32 v146, v87, v146
	v_mfma_f32_16x16x32_bf16 v[40:43], v[72:75], v[68:71], v[40:43]
	ds_read_b64_tr_b16 v[68:69], v147 offset:8192
	ds_read_b64_tr_b16 v[70:71], v147 offset:12288
	v_cvt_pk_bf16_f32 v80, v80, v81
	v_cvt_pk_bf16_f32 v81, v82, v83
	v_cvt_pk_bf16_f32 v82, v84, v85
	v_cvt_pk_bf16_f32 v83, v86, v87
	s_waitcnt lgkmcnt(10)
	v_mfma_f32_16x16x32_bf16 v[12:15], v[64:67], v[224:227], v[12:15]
	v_add_f32_e32 v155, v155, v146
	v_subrev_f32_e32 v88, s66, v88
	v_subrev_f32_e32 v89, s66, v89
	v_exp_f32_e32 v88, v88
	ds_read_b64_tr_b16 v[84:85], v147 offset:8448
	ds_read_b64_tr_b16 v[86:87], v147 offset:12544
	v_mfma_f32_16x16x32_bf16 v[44:47], v[72:75], v[224:227], v[44:47]
	ds_read_b64_tr_b16 v[224:225], v147 offset:8704
	ds_read_b64_tr_b16 v[226:227], v147 offset:12800
	v_subrev_f32_e32 v90, s66, v90
	v_exp_f32_e32 v89, v89
	v_subrev_f32_e32 v91, s66, v91
	v_exp_f32_e32 v90, v90
	s_waitcnt lgkmcnt(12)
	v_mfma_f32_16x16x32_bf16 v[16:19], v[64:67], v[76:79], v[16:19]
	v_add_f32_e32 v148, v88, v148
	v_subrev_f32_e32 v92, s66, v92
	v_exp_f32_e32 v91, v91
	v_add_f32_e32 v148, v89, v148
	v_mfma_f32_16x16x32_bf16 v[48:51], v[72:75], v[76:79], v[48:51]
	ds_read_b64_tr_b16 v[76:77], v147 offset:8960
	ds_read_b64_tr_b16 v[78:79], v147 offset:13056
	v_subrev_f32_e32 v93, s66, v93
	v_exp_f32_e32 v92, v92
	v_add_f32_e32 v148, v90, v148
	s_waitcnt lgkmcnt(12)
	v_mfma_f32_16x16x32_bf16 v[20:23], v[64:67], v[240:243], v[20:23]
	v_subrev_f32_e32 v94, s66, v94
	v_exp_f32_e32 v93, v93
	v_add_f32_e32 v148, v91, v148
	v_mfma_f32_16x16x32_bf16 v[52:55], v[72:75], v[240:243], v[52:55]
	ds_read_b64_tr_b16 v[240:241], v147 offset:9216
	ds_read_b64_tr_b16 v[242:243], v147 offset:13312
	v_subrev_f32_e32 v95, s66, v95
	v_exp_f32_e32 v94, v94
	v_add_f32_e32 v148, v92, v148
	s_waitcnt lgkmcnt(12)
	v_mfma_f32_16x16x32_bf16 v[24:27], v[64:67], v[244:247], v[24:27]
	v_exp_f32_e32 v95, v95
	v_add_f32_e32 v148, v93, v148
	v_add_f32_e32 v148, v94, v148
	v_mfma_f32_16x16x32_bf16 v[56:59], v[72:75], v[244:247], v[56:59]
	ds_read_b64_tr_b16 v[244:245], v147 offset:9472
	ds_read_b64_tr_b16 v[246:247], v147 offset:13568
	v_add_f32_e32 v148, v95, v148
	v_cvt_pk_bf16_f32 v88, v88, v89
	v_cvt_pk_bf16_f32 v89, v90, v91
	s_waitcnt lgkmcnt(12)
	v_mfma_f32_16x16x32_bf16 v[28:31], v[64:67], v[216:219], v[28:31]
	v_cvt_pk_bf16_f32 v90, v92, v93
	v_cvt_pk_bf16_f32 v91, v94, v95
	v_add_f32_e32 v149, v149, v148
	ds_read_b64_tr_b16 v[92:93], v147 offset:9728
	ds_read_b64_tr_b16 v[94:95], v147 offset:13824
	v_mfma_f32_16x16x32_bf16 v[60:63], v[72:75], v[216:219], v[60:63]
	s_waitcnt lgkmcnt(12)
	v_mfma_f32_16x16x32_bf16 v[0:3], v[80:83], v[68:71], v[0:3]
	v_mfma_f32_16x16x32_bf16 v[32:35], v[88:91], v[68:71], v[32:35]
	ds_read_b64_tr_b16 v[216:217], v147 offset:9984
	ds_read_b64_tr_b16 v[218:219], v147 offset:14080
	s_waitcnt lgkmcnt(12)
	v_mfma_f32_16x16x32_bf16 v[4:7], v[80:83], v[84:87], v[4:7]
	v_mfma_f32_16x16x32_bf16 v[36:39], v[88:91], v[84:87], v[36:39]
	s_waitcnt lgkmcnt(10)
	v_mfma_f32_16x16x32_bf16 v[8:11], v[80:83], v[224:227], v[8:11]
	v_lshl_add_u64 v[166:167], s[68:69], 0, v[164:165]
	s_add_i32 m0, s43, 0x2000
	v_lshl_add_u64 v[166:167], v[166:167], 0, s[20:21]
	global_load_lds_dwordx4 v[166:167], off
	v_mfma_f32_16x16x32_bf16 v[40:43], v[88:91], v[224:227], v[40:43]
	s_waitcnt lgkmcnt(8)
	v_mfma_f32_16x16x32_bf16 v[12:15], v[80:83], v[76:79], v[12:15]
	v_mfma_f32_16x16x32_bf16 v[44:47], v[88:91], v[76:79], v[44:47]
	s_waitcnt lgkmcnt(6)
	v_mfma_f32_16x16x32_bf16 v[16:19], v[80:83], v[240:243], v[16:19]
	v_mfma_f32_16x16x32_bf16 v[48:51], v[88:91], v[240:243], v[48:51]
	s_waitcnt lgkmcnt(4)
	v_mfma_f32_16x16x32_bf16 v[20:23], v[80:83], v[244:247], v[20:23]
	v_mfma_f32_16x16x32_bf16 v[52:55], v[88:91], v[244:247], v[52:55]
	s_waitcnt lgkmcnt(2)
	v_mfma_f32_16x16x32_bf16 v[24:27], v[80:83], v[92:95], v[24:27]
	v_mfma_f32_16x16x32_bf16 v[56:59], v[88:91], v[92:95], v[56:59]
	s_waitcnt lgkmcnt(0)
	v_mfma_f32_16x16x32_bf16 v[28:31], v[80:83], v[216:219], v[28:31]
	v_mfma_f32_16x16x32_bf16 v[60:63], v[88:91], v[216:219], v[60:63]
	s_mov_b32 s71, 1
	s_branch .LBB0_137
